# phase0 balance: rotate starting block of WQ/WKV/WGU/WDN tile loops so per-block extra tiles <= 4 (was 7 on blocks 0-31)
# baseline (speedup 1.0000x reference)
; DI void phase_weights(const Ctx& c) {
;   bf16* tile = (bf16*)c.smem;
;   for (int layer = 0; layer < 2; ++layer) {
;     bf16* W = (bf16*)(c.ws + OFF_W + layer * SZ_WL);
;     const float* w_in = c.in[6] + (size_t)layer * DM * DIN;
;     const float* g_mix = c.in[2] + layer * DM;
;     const float* g_ffn = c.in[4] + layer * DM;
;     convT(W + EO_WIN, 4096, 1024, w_in, w_in, DIN, g_mix, [](int n) -> int {
;       if (n < 1984) return n;
;       if (n < 2048) return (n < 2000) ? 4032 + (n - 1984) : -1;
;       if (n < 3584) return 1984 + (n - 2048);
;       return 3520 + (n - 3584); }, tile);
;     convT(W + EO_WGT, 3072, 1024, w_in, w_in, DIN, g_mix, [](int n) -> int { return 4048 + n; }, tile);
;     convT(W + EO_WQ, 768, 256, c.in[17] + (size_t)layer * 256 * 768, nullptr, 768, c.in[16] + layer * 256, [](int n) -> int { return n; }, tile);
;     convT(W + EO_WKV, 1024, 128, c.in[19] + (size_t)layer * 128 * 1024, nullptr, 1024, c.in[18] + layer * 128, [](int n) -> int { return n; }, tile);
;     for (int b = 0; b < 3; ++b)
;       convT(W + EO_WBR + (size_t)b * 1024 * 512, 1024, 512, c.in[24] + ((size_t)layer * 3 + b) * 512 * 1024, nullptr, 1024, nullptr, [](int n) -> int { return n; }, tile);
;     convT(W + EO_WOUT, 1024, 1024, c.in[25] + (size_t)layer * DM * DM, nullptr, 1024, nullptr, [](int n) -> int { return n; }, tile);
;     convT(W + EO_WGU, 5632, 1024, c.in[26] + (size_t)layer * DM * DFF, c.in[27] + (size_t)layer * DM * DFF, DFF, g_ffn, [](int n) -> int {
;       const int grp = n >> 5, w = n & 31;
;       return (w < 16) ? (grp * 16 + w) : ((grp * 16 + w - 16) | (1 << 28)); }, tile);
;     convT(W + EO_WDN, 1024, 2816, c.in[28] + (size_t)layer * DFF * DM, nullptr, 1024, nullptr, [](int n) -> int { return n; }, tile);
.LBB0_10:
	s_or_b64 exec, exec, s[4:5]
	s_load_dwordx16 s[80:95], s[0:1], 0x0
	s_load_dwordx16 s[36:51], s[0:1], 0x40
	s_cmpk_lt_i32 s74, 0x400
	s_cselect_b64 s[20:21], -1, 0
	s_cmpk_lt_i32 s74, 0x300
	s_cselect_b64 s[22:23], -1, 0
	s_waitcnt lgkmcnt(0)
	v_writelane_b32 v229, s36, 4
	s_add_i32 s100, s74, 128
	s_and_b32 s100, s100, 0xff
	s_cmp_eq_u32 s76, 0x100
	s_cselect_b32 s100, s100, s74
	s_cmp_lt_i32 s100, 48
	s_cselect_b64 s[24:25], -1, 0
	v_writelane_b32 v229, s37, 5
	v_writelane_b32 v229, s38, 6
	v_writelane_b32 v229, s39, 7
	v_writelane_b32 v229, s40, 8
	v_writelane_b32 v229, s41, 9
	v_writelane_b32 v229, s42, 10
	v_writelane_b32 v229, s43, 11
	v_writelane_b32 v229, s44, 12
	v_writelane_b32 v229, s45, 13
	v_writelane_b32 v229, s46, 14
	v_writelane_b32 v229, s47, 15
	v_writelane_b32 v229, s48, 16
	v_writelane_b32 v229, s49, 17
	v_writelane_b32 v229, s50, 18
	s_add_i32 s100, s74, 80
	s_and_b32 s100, s100, 0xff
	s_cmp_eq_u32 s76, 0x100
	s_cselect_b32 s100, s100, s74
	s_cmp_lt_i32 s100, 32
	v_writelane_b32 v229, s51, 19
	s_load_dwordx16 s[40:55], s[0:1], 0x80
	s_cselect_b64 s[26:27], -1, 0
	s_cmpk_lt_i32 s74, 0x80
	s_cselect_b64 s[28:29], -1, 0
	s_cmpk_lt_i32 s74, 0x100
	s_cselect_b64 s[4:5], -1, 0
	s_cmpk_gt_i32 s74, 0x57f
	v_writelane_b32 v229, s4, 20
	s_cselect_b64 s[30:31], -1, 0
	s_cmpk_lt_i32 s74, 0x2c0
	v_writelane_b32 v229, s5, 21
	s_cselect_b64 s[34:35], -1, 0
	s_cmp_lg_u64 s[84:85], 0
	s_cselect_b64 s[36:37], -1, 0
	s_waitcnt lgkmcnt(0)
	s_cmp_lg_u64 s[40:41], 0
	v_writelane_b32 v229, s40, 22
	s_cselect_b64 s[38:39], -1, 0
	s_cmp_lg_u64 s[44:45], 0
	v_writelane_b32 v229, s41, 23
	v_writelane_b32 v229, s42, 24
	v_writelane_b32 v229, s43, 25
	v_writelane_b32 v229, s44, 26
	v_writelane_b32 v229, s45, 27
	v_writelane_b32 v229, s46, 28
	v_writelane_b32 v229, s47, 29
	v_writelane_b32 v229, s48, 30
	v_writelane_b32 v229, s49, 31
	v_writelane_b32 v229, s50, 32
	v_writelane_b32 v229, s51, 33
	v_writelane_b32 v229, s52, 34
	v_writelane_b32 v229, s53, 35
	v_writelane_b32 v229, s54, 36
	v_writelane_b32 v229, s55, 37
	s_cselect_b64 s[40:41], -1, 0
	s_cmp_lg_u64 s[88:89], 0
	v_writelane_b32 v229, s80, 38
	s_mov_b32 s43, 0
	v_and_b32_e32 v186, 0x3ff, v0
	v_writelane_b32 v229, s81, 39
	v_writelane_b32 v229, s82, 40
	v_writelane_b32 v229, s83, 41
	v_writelane_b32 v229, s84, 42
	v_writelane_b32 v229, s85, 43
	v_writelane_b32 v229, s86, 44
	v_writelane_b32 v229, s87, 45
	v_writelane_b32 v229, s88, 46
	v_writelane_b32 v229, s89, 47
	v_writelane_b32 v229, s90, 48
	v_writelane_b32 v229, s91, 49
	v_writelane_b32 v229, s92, 50
	v_writelane_b32 v229, s93, 51
	s_mov_b64 s[46:47], -1
	s_cselect_b64 s[44:45], -1, 0
	s_movk_i32 s33, 0x1000
	v_mov_b32_e32 v9, 0
	s_movk_i32 s60, 0x84
	s_movk_i32 s61, 0x5ff
	s_movk_i32 s62, 0xff7e
	s_movk_i32 s63, 0x6f40
	s_movk_i32 s64, 0xdff
	v_mov_b32_e32 v16, 0x50
	s_mov_b32 s42, s43
	s_movk_i32 s65, 0x1600
	v_writelane_b32 v229, s94, 52
	s_barrier
	v_writelane_b32 v229, s95, 53
	s_branch .LBB0_12

; template <class F>
; DI void convT(bf16* dst, int N, int K, const float* src, const float* src2, int ld, const float* gain, F cmap, bf16* tile) {
;     ...
;   for (int it = blockIdx.x; it < tilesN * tilesK; it += gridDim.x) {
;     const int tn = it % tilesN, tk = it / tilesN;
; DI void phase_weights(const Ctx& c) {
;     ...
;     convT(W + EO_WQ, 768, 256, c.in[17] + (size_t)layer * 256 * 768, nullptr, 768, c.in[16] + layer * 256, [](int n) -> int { return n; }, tile);
.LBB0_45:
	v_mov_b32_e32 v0, v186
	s_andn2_b64 vcc, exec, s[24:25]
	s_cbranch_vccnz .LBB0_65
	v_readlane_b32 s80, v229, 22
	s_mul_i32 s0, s42, 0xc0000
	v_readlane_b32 s82, v229, 24
	s_load_dword s4, s[2:3], 0x10
	v_readlane_b32 s83, v229, 25
	s_add_u32 s8, s82, s0
	s_addc_u32 s9, s83, 0
	s_lshl_b32 s0, s42, 8
	s_mov_b32 s1, s43
	s_lshl_b64 s[0:1], s[0:1], 2
	v_readlane_b32 s81, v229, 23
	s_add_u32 s50, s80, s0
	s_addc_u32 s51, s81, s1
	s_waitcnt lgkmcnt(0)
	s_lshr_b32 s4, s4, 16
	s_and_b32 s4, s4, 0xffff
	s_cmp_lg_u32 s4, 0
	v_and_b32_e32 v13, 63, v0
	v_max_i32_e32 v1, 0xe00, v0
	s_cselect_b64 s[4:5], -1, 0
	v_lshlrev_b32_e32 v8, 1, v13
	v_sub_u32_e32 v1, v1, v0
	s_cmp_lg_u64 s[4:5], 0
	v_lshl_add_u64 v[2:3], s[48:49], 0, v[8:9]
	s_mov_b64 s[4:5], 0xe40000
	v_add_u32_e32 v1, 0x1ff, v1
	v_lshl_add_u64 v[10:11], v[2:3], 0, s[4:5]
	v_lshrrev_b32_e32 v2, 9, v1
	v_add_u32_e32 v4, 1, v2
	v_mad_u32_u24 v17, v13, s60, v16
	v_and_b32_e32 v18, 0xfffffc, v4
	v_cmp_gt_i32_e64 s[0:1], s33, v0
	s_addc_u32 s58, s76, 0
	v_cmp_lt_u32_e64 s[4:5], s61, v1
	v_lshl_add_u32 v19, v18, 9, v0
	v_add_u32_e32 v3, 0x600, v0
	v_add_u32_e32 v2, 0x400, v0
	v_add_u32_e32 v1, 0x200, v0
	v_mad_i32_i24 v12, v13, s62, v17
	v_cmp_ne_u32_e64 s[6:7], v4, v18
	s_add_i32 s59, s74, 128
	s_and_b32 s59, s59, 0xff
	s_cmp_eq_u32 s76, 0x100
	s_cselect_b32 s59, s59, s74
	v_readlane_b32 s84, v229, 26
	v_readlane_b32 s85, v229, 27
	v_readlane_b32 s86, v229, 28
	v_readlane_b32 s87, v229, 29
	v_readlane_b32 s88, v229, 30
	v_readlane_b32 s89, v229, 31
	v_readlane_b32 s90, v229, 32
	v_readlane_b32 s91, v229, 33
	v_readlane_b32 s92, v229, 34
	v_readlane_b32 s93, v229, 35
	v_readlane_b32 s94, v229, 36
	v_readlane_b32 s95, v229, 37
	s_branch .LBB0_48

; template <class F>
; DI void convT(bf16* dst, int N, int K, const float* src, const float* src2, int ld, const float* gain, F cmap, bf16* tile) {
;     ...
;   for (int it = blockIdx.x; it < tilesN * tilesK; it += gridDim.x) {
;     const int tn = it % tilesN, tk = it / tilesN;
; DI void phase_weights(const Ctx& c) {
;     ...
;     convT(W + EO_WKV, 1024, 128, c.in[19] + (size_t)layer * 128 * 1024, nullptr, 1024, c.in[18] + layer * 128, [](int n) -> int { return n; }, tile);
.LBB0_65:
	v_mov_b32_e32 v0, v186
	s_andn2_b64 vcc, exec, s[26:27]
	s_cbranch_vccnz .LBB0_85
	v_readlane_b32 s80, v229, 22
	s_lshl_b64 s[0:1], s[42:43], 19
	v_readlane_b32 s86, v229, 28
	s_load_dword s4, s[2:3], 0x10
	v_readlane_b32 s87, v229, 29
	s_add_u32 s8, s86, s0
	s_addc_u32 s9, s87, s1
	s_lshl_b32 s0, s42, 7
	s_mov_b32 s1, s43
	v_readlane_b32 s84, v229, 26
	s_lshl_b64 s[0:1], s[0:1], 2
	v_readlane_b32 s85, v229, 27
	s_add_u32 s50, s84, s0
	s_addc_u32 s51, s85, s1
	s_waitcnt lgkmcnt(0)
	s_lshr_b32 s4, s4, 16
	s_and_b32 s4, s4, 0xffff
	s_cmp_lg_u32 s4, 0
	v_and_b32_e32 v13, 63, v0
	v_max_i32_e32 v1, 0xe00, v0
	s_cselect_b64 s[4:5], -1, 0
	v_lshlrev_b32_e32 v8, 1, v13
	v_sub_u32_e32 v1, v1, v0
	s_cmp_lg_u64 s[4:5], 0
	v_lshl_add_u64 v[2:3], s[48:49], 0, v[8:9]
	s_mov_b64 s[4:5], 0xea0000
	v_add_u32_e32 v1, 0x1ff, v1
	v_lshl_add_u64 v[10:11], v[2:3], 0, s[4:5]
	v_lshrrev_b32_e32 v2, 9, v1
	v_add_u32_e32 v4, 1, v2
	v_mad_u32_u24 v17, v13, s60, v16
	v_and_b32_e32 v18, 0xfffffc, v4
	v_cmp_gt_i32_e64 s[0:1], s33, v0
	s_addc_u32 s58, s76, 0
	v_cmp_lt_u32_e64 s[4:5], s61, v1
	v_lshl_add_u32 v19, v18, 9, v0
	v_add_u32_e32 v3, 0x600, v0
	v_add_u32_e32 v2, 0x400, v0
	v_add_u32_e32 v1, 0x200, v0
	v_mad_i32_i24 v12, v13, s62, v17
	v_cmp_ne_u32_e64 s[6:7], v4, v18
	s_add_i32 s59, s74, 80
	s_and_b32 s59, s59, 0xff
	s_cmp_eq_u32 s76, 0x100
	s_cselect_b32 s59, s59, s74
	v_readlane_b32 s81, v229, 23
	v_readlane_b32 s82, v229, 24
	v_readlane_b32 s83, v229, 25
	v_readlane_b32 s88, v229, 30
	v_readlane_b32 s89, v229, 31
	v_readlane_b32 s90, v229, 32
	v_readlane_b32 s91, v229, 33
	v_readlane_b32 s92, v229, 34
	v_readlane_b32 s93, v229, 35
	v_readlane_b32 s94, v229, 36
	v_readlane_b32 s95, v229, 37
	s_branch .LBB0_68

; template <class F>
; DI void convT(bf16* dst, int N, int K, const float* src, const float* src2, int ld, const float* gain, F cmap, bf16* tile) {
;     ...
;   for (int it = blockIdx.x; it < tilesN * tilesK; it += gridDim.x) {
;     const int tn = it % tilesN, tk = it / tilesN;
; DI void phase_weights(const Ctx& c) {
;     ...
;     convT(W + EO_WGU, 5632, 1024, c.in[26] + (size_t)layer * DM * DFF, c.in[27] + (size_t)layer * DM * DFF, DFF, g_ffn, [](int n) -> int {
;       const int grp = n >> 5, w = n & 31;
;       return (w < 16) ? (grp * 16 + w) : ((grp * 16 + w - 16) | (1 << 28)); }, tile);
.LBB0_157:
	s_andn2_b64 vcc, exec, s[0:1]
	s_cbranch_vccnz .LBB0_174
	s_load_dword s4, s[2:3], 0x10
	s_add_u32 s50, s88, s10
	v_and_b32_e32 v17, 63, v0
	v_max_i32_e32 v1, 0xe00, v0
	s_addc_u32 s51, s89, s11
	s_waitcnt lgkmcnt(0)
	s_lshr_b32 s4, s4, 16
	v_lshlrev_b32_e32 v8, 1, v17
	v_sub_u32_e32 v1, v1, v0
	s_and_b32 s4, s4, 0xffff
	v_lshl_add_u64 v[2:3], s[48:49], 0, v[8:9]
	s_mov_b64 s[6:7], 0x13e0000
	v_add_u32_e32 v1, 0x1ff, v1
	s_cmp_lg_u32 s4, 0
	v_lshl_add_u64 v[10:11], v[2:3], 0, s[6:7]
	v_lshrrev_b32_e32 v2, 9, v1
	s_cselect_b64 s[4:5], -1, 0
	v_add_u32_e32 v4, 1, v2
	v_and_b32_e32 v13, 31, v0
	s_cmp_lg_u64 s[4:5], 0
	v_mad_u32_u24 v19, v17, s60, v16
	v_and_b32_e32 v20, 0xfffffc, v4
	v_cmp_gt_i32_e64 s[0:1], s33, v0
	s_addc_u32 s58, s76, 0
	v_subrev_co_u32_e64 v18, s[4:5], 16, v13
	v_cmp_lt_u32_e64 s[6:7], s61, v1
	v_lshl_add_u32 v21, v20, 9, v0
	v_add_u32_e32 v3, 0x600, v0
	v_add_u32_e32 v2, 0x400, v0
	v_add_u32_e32 v1, 0x200, v0
	v_mad_i32_i24 v12, v17, s62, v19
	v_cmp_ne_u32_e64 s[8:9], v4, v20
	s_add_i32 s59, s74, 128
	s_and_b32 s59, s59, 0xff
	s_cmp_eq_u32 s76, 0x100
	s_cselect_b32 s59, s59, s74
	s_branch .LBB0_160

; template <class F>
; DI void convT(bf16* dst, int N, int K, const float* src, const float* src2, int ld, const float* gain, F cmap, bf16* tile) {
;     ...
;   for (int it = blockIdx.x; it < tilesN * tilesK; it += gridDim.x) {
;     const int tn = it % tilesN, tk = it / tilesN;
; DI void phase_weights(const Ctx& c) {
;     ...
;     convT(W + EO_WDN, 1024, 2816, c.in[28] + (size_t)layer * DFF * DM, nullptr, 1024, nullptr, [](int n) -> int { return n; }, tile);
.LBB0_174:
	s_xor_b64 s[8:9], s[46:47], -1
	v_mov_b32_e32 v0, v186
	s_andn2_b64 vcc, exec, s[34:35]
	s_cbranch_vccnz .LBB0_11
	s_load_dword s4, s[2:3], 0x10
	v_readlane_b32 s52, v229, 0
	v_readlane_b32 s53, v229, 1
	s_add_u32 s10, s52, s42
	s_addc_u32 s11, s53, s43
	s_waitcnt lgkmcnt(0)
	s_lshr_b32 s4, s4, 16
	s_and_b32 s4, s4, 0xffff
	v_and_b32_e32 v13, 63, v0
	s_cmp_lg_u32 s4, 0
	v_max_i32_e32 v1, 0xe00, v0
	s_cselect_b64 s[4:5], -1, 0
	v_lshlrev_b32_e32 v8, 1, v13
	v_sub_u32_e32 v1, v1, v0
	s_cmp_lg_u64 s[4:5], 0
	v_lshl_add_u64 v[2:3], s[48:49], 0, v[8:9]
	s_mov_b64 s[4:5], 0x1ee0000
	v_add_u32_e32 v1, 0x1ff, v1
	v_lshl_add_u64 v[10:11], v[2:3], 0, s[4:5]
	v_lshrrev_b32_e32 v2, 9, v1
	v_add_u32_e32 v4, 1, v2
	v_mad_u32_u24 v17, v13, s60, v16
	v_and_b32_e32 v18, 0xfffffc, v4
	v_cmp_gt_i32_e64 s[0:1], s33, v0
	s_addc_u32 s42, s76, 0
	v_cmp_lt_u32_e64 s[4:5], s61, v1
	v_lshl_add_u32 v19, v18, 9, v0
	v_add_u32_e32 v3, 0x600, v0
	v_add_u32_e32 v2, 0x400, v0
	v_add_u32_e32 v1, 0x200, v0
	v_mad_i32_i24 v12, v13, s62, v17
	v_cmp_ne_u32_e64 s[6:7], v4, v18
	s_add_i32 s52, s74, 128
	s_and_b32 s52, s52, 0xff
	s_cmp_eq_u32 s76, 0x100
	s_cselect_b32 s52, s52, s74
	v_readlane_b32 s54, v229, 2
	v_readlane_b32 s55, v229, 3
	s_branch .LBB0_177
